# final rmsnorm weights preloaded; prenorm row loops: all 16 loads of a row issued up front, row pointer via scalar load (no per-row store drain)
# speedup vs baseline: 1.0633x; 1.0026x over previous
; __device__ void ph_prenorm(const Params& p, int l, int g) {
;     ...
;   for (int row = gw; row < TG; row += nw) {
;     int bl = row / TPB, pp = row % TPB, b = g * GB + bl;
;     const float* src; int mrow;
;     if (pp < CTX) { src = (l == 0 ? p.ctx : p.ctxs) + ((long)b * CTX + pp) * D; mrow = 16; }
;     else { src = (l == 0 ? p.x : p.out) + ((long)b * SEQ + (pp - CTX)) * D; mrow = b; }
;     const float* md = p.mod + ((long)l * 17 + mrow) * 3072;
;     float4 v[4]; float ss = 0.f;
; #pragma unroll
;     for (int i = 0; i < 4; ++i) {
;       v[i] = ((const float4*)src)[lane + 64 * i];
;       ss += v[i].x * v[i].x + v[i].y * v[i].y + v[i].z * v[i].z + v[i].w * v[i].w;
;     }
;     ss = wave_sum(ss);
;     float rs = rsqrtf(ss * (1.f / D) + 1e-6f);
; #pragma unroll
;     for (int i = 0; i < 4; ++i) {
;       int idx = (lane + 64 * i) * 4;
;       float4 g4 = *(const float4*)(p.norm_g + l * D + idx);
;       float4 sh = *(const float4*)(md + idx);
;       float4 sc = *(const float4*)(md + D + idx);
;       float h0 = v[i].x * rs * g4.x * (1.f + sc.x) + sh.x;
;       float h1 = v[i].y * rs * g4.y * (1.f + sc.y) + sh.y;
;       float h2 = v[i].z * rs * g4.z * (1.f + sc.z) + sh.z;
;       float h3 = v[i].w * rs * g4.w * (1.f + sc.w) + sh.w;
;       uint2 o; o.x = pack2(h0, h1); o.y = pack2(h2, h3);
;       *(uint2*)(p.hbuf + ((long)(idx >> 5) * TG + row) * 32 + (idx & 31)) = o;
;     }
;   }
.LBB0_118:
	s_or_b64 exec, exec, s[42:43]
	s_nop 1
	v_readfirstlane_b32 s100, v34
	v_readfirstlane_b32 s101, v35
	s_nop 3
	s_load_dwordx2 s[100:101], s[100:101], 0x0
	v_lshlrev_b64 v[28:29], v32, v[28:29]
	v_lshlrev_b64 v[30:31], 12, v[30:31]
	v_lshl_add_u64 v[26:27], s[90:91], 0, v[26:27]
	s_mov_b64 s[12:13], 0x1000
	v_lshl_add_u64 v[62:63], v[26:27], 0, s[12:13]
	v_lshl_add_u64 v[50:51], v[62:63], 0, v[18:19]
	v_lshl_add_u64 v[64:65], v[26:27], 0, v[18:19]
	s_movk_i32 s10, 0x23ff
	s_waitcnt lgkmcnt(0)
	v_mov_b64_e32 v[34:35], s[100:101]
	v_lshl_add_u64 v[28:29], v[34:35], 0, v[28:29]
	v_lshl_add_u64 v[28:29], v[28:29], 0, v[30:31]
	v_lshl_add_u64 v[46:47], v[28:29], 0, v[16:17]
	global_load_dwordx4 v[28:31], v[46:47], off
	global_load_dwordx4 v[32:35], v[46:47], off offset:1024
	global_load_dwordx4 v[42:45], v[46:47], off offset:2048
	s_nop 0
	global_load_dwordx4 v[46:49], v[46:47], off offset:3072
	s_nop 0
	global_load_dwordx4 v[50:53], v[50:51], off
	s_nop 0
	global_load_dwordx4 v[54:57], v[12:13], off
	global_load_dwordx4 v[58:61], v[64:65], off
	global_load_dwordx4 v[200:203], v[12:13], off offset:1024
	v_mov_b32_e32 v236, v20
	v_mov_b32_e32 v237, 0
	v_lshl_add_u64 v[236:237], v[62:63], 0, v[236:237]
	global_load_dwordx4 v[204:207], v[236:237], off
	global_load_dwordx4 v[208:211], v[64:65], off offset:1024
	global_load_dwordx4 v[212:215], v[12:13], off offset:2048
	v_mov_b32_e32 v238, v22
	v_mov_b32_e32 v239, 0
	v_lshl_add_u64 v[238:239], v[62:63], 0, v[238:239]
	global_load_dwordx4 v[216:219], v[238:239], off
	global_load_dwordx4 v[220:223], v[64:65], off offset:2048
	global_load_dwordx4 v[224:227], v[12:13], off offset:3072
	v_mov_b32_e32 v244, v24
	v_mov_b32_e32 v245, 0
	v_lshl_add_u64 v[244:245], v[62:63], 0, v[244:245]
	global_load_dwordx4 v[228:231], v[244:245], off
	global_load_dwordx4 v[232:235], v[64:65], off offset:3072
	s_waitcnt vmcnt(15)
	v_mov_b32_e32 v70, v29
	s_waitcnt vmcnt(14)
	v_mov_b32_e32 v71, v33
	v_mov_b32_e32 v68, v28
	v_mov_b32_e32 v69, v32
	s_waitcnt vmcnt(13)
	v_mov_b32_e32 v78, v43
	s_waitcnt vmcnt(12)
	v_mov_b32_e32 v79, v47
	v_pk_mul_f32 v[70:71], v[70:71], v[70:71]
	v_mov_b32_e32 v26, v30
	v_mov_b32_e32 v27, v34
	v_mov_b32_e32 v76, v42
	v_mov_b32_e32 v77, v46
	v_pk_mul_f32 v[78:79], v[78:79], v[78:79]
	v_pk_fma_f32 v[68:69], v[68:69], v[68:69], v[70:71]
	v_mov_b32_e32 v66, v31
	v_mov_b32_e32 v67, v35
	v_mov_b32_e32 v72, v44
	v_mov_b32_e32 v73, v48
	v_pk_fma_f32 v[70:71], v[76:77], v[76:77], v[78:79]
	v_pk_fma_f32 v[26:27], v[26:27], v[26:27], v[68:69]
	v_mov_b32_e32 v74, v45
	v_mov_b32_e32 v75, v49
	v_pk_fma_f32 v[68:69], v[72:73], v[72:73], v[70:71]
	v_pk_fma_f32 v[26:27], v[66:67], v[66:67], v[26:27]
	v_pk_fma_f32 v[66:67], v[74:75], v[74:75], v[68:69]
	v_add_f32_e32 v0, v26, v27
	v_add_f32_e32 v0, v0, v66
	v_add_f32_e32 v0, v0, v67
	ds_bpermute_b32 v3, v36, v0
	s_waitcnt vmcnt(11)
	v_pk_add_f32 v[50:51], v[50:51], 1.0 op_sel_hi:[1,0]
	v_pk_add_f32 v[52:53], v[52:53], 1.0 op_sel_hi:[1,0]
	v_lshl_add_u64 v[66:67], v[62:63], 0, v[20:21]
	s_waitcnt lgkmcnt(0)
	v_add_f32_e32 v0, v0, v3
	ds_bpermute_b32 v3, v37, v0
	s_waitcnt lgkmcnt(0)
	v_add_f32_e32 v0, v0, v3
	ds_bpermute_b32 v3, v38, v0
	s_waitcnt lgkmcnt(0)
	v_add_f32_e32 v0, v0, v3
	ds_bpermute_b32 v3, v39, v0
	s_waitcnt lgkmcnt(0)
	v_add_f32_e32 v0, v0, v3
	ds_bpermute_b32 v3, v40, v0
	s_waitcnt lgkmcnt(0)
	v_add_f32_e32 v0, v0, v3
	ds_bpermute_b32 v68, v41, v0
	v_ashrrev_i32_e32 v3, 31, v2
	v_lshl_add_u64 v[26:27], v[2:3], 0, v[4:5]
	v_lshlrev_b64 v[26:27], 6, v[26:27]
	v_lshl_add_u64 v[26:27], v[14:15], 0, v[26:27]
	s_waitcnt lgkmcnt(0)
	v_add_f32_e32 v0, v0, v68
	v_fmamk_f32 v0, v0, 0x3a800000, v168
	v_mul_f32_e32 v68, 0x4b800000, v0
	v_cmp_gt_f32_e32 vcc, s25, v0
	s_nop 1
	v_cndmask_b32_e32 v0, v0, v68, vcc
	v_rsq_f32_e32 v0, v0
	s_nop 0
	v_mul_f32_e32 v68, 0x45800000, v0
	v_cndmask_b32_e32 v0, v0, v68, vcc
	v_pk_mul_f32 v[28:29], v[28:29], v[0:1] op_sel_hi:[1,0]
	v_pk_mul_f32 v[30:31], v[30:31], v[0:1] op_sel_hi:[1,0]
	s_waitcnt vmcnt(10)
	v_pk_mul_f32 v[28:29], v[54:55], v[28:29]
	v_pk_mul_f32 v[30:31], v[56:57], v[30:31]
	s_waitcnt vmcnt(9)
	v_pk_fma_f32 v[28:29], v[50:51], v[28:29], v[58:59]
	v_pk_fma_f32 v[30:31], v[30:31], v[52:53], v[60:61]
	v_cvt_pk_bf16_f32 v28, v28, v29
	v_cvt_pk_bf16_f32 v29, v30, v31
	global_store_dwordx2 v[26:27], v[28:29], off
	s_nop 0
	v_pk_mul_f32 v[32:33], v[32:33], v[0:1] op_sel_hi:[1, 0]
	v_pk_mul_f32 v[34:35], v[34:35], v[0:1] op_sel_hi:[1, 0]
	v_lshl_add_u64 v[30:31], v[2:3], 0, v[6:7]
	v_lshlrev_b64 v[30:31], 6, v[30:31]
	v_lshl_add_u64 v[30:31], v[14:15], 0, v[30:31]
	v_lshl_add_u64 v[58:59], v[62:63], 0, v[22:23]
	v_pk_mul_f32 v[42:43], v[42:43], v[0:1] op_sel_hi:[1, 0]
	v_pk_mul_f32 v[44:45], v[44:45], v[0:1] op_sel_hi:[1, 0]
	v_pk_mul_f32 v[46:47], v[46:47], v[0:1] op_sel_hi:[1, 0]
	v_pk_mul_f32 v[48:49], v[48:49], v[0:1] op_sel_hi:[1, 0]
	s_waitcnt vmcnt(9)
	v_pk_mul_f32 v[26:27], v[32:33], v[200:201]
	s_waitcnt vmcnt(8)
	v_pk_add_f32 v[32:33], v[204:205], 1.0 op_sel_hi:[1, 0]
	v_pk_mul_f32 v[28:29], v[34:35], v[202:203]
	v_pk_add_f32 v[34:35], v[206:207], 1.0 op_sel_hi:[1, 0]
	s_waitcnt vmcnt(7)
	v_pk_fma_f32 v[26:27], v[26:27], v[32:33], v[208:209]
	v_pk_fma_f32 v[28:29], v[28:29], v[34:35], v[210:211]
	v_cvt_pk_bf16_f32 v26, v26, v27
	v_cvt_pk_bf16_f32 v27, v28, v29
	global_store_dwordx2 v[30:31], v[26:27], off
	s_nop 0
	v_lshl_add_u64 v[34:35], v[2:3], 0, v[8:9]
	v_lshlrev_b64 v[34:35], 6, v[34:35]
	v_lshl_add_u64 v[34:35], v[14:15], 0, v[34:35]
	v_lshl_add_u64 v[54:55], v[62:63], 0, v[24:25]
	s_waitcnt vmcnt(7)
	v_pk_mul_f32 v[26:27], v[42:43], v[212:213]
	s_waitcnt vmcnt(6)
	v_pk_add_f32 v[30:31], v[216:217], 1.0 op_sel_hi:[1, 0]
	v_pk_mul_f32 v[28:29], v[44:45], v[214:215]
	v_pk_add_f32 v[32:33], v[218:219], 1.0 op_sel_hi:[1, 0]
	s_waitcnt vmcnt(5)
	v_pk_fma_f32 v[26:27], v[26:27], v[30:31], v[220:221]
	v_pk_fma_f32 v[28:29], v[28:29], v[32:33], v[222:223]
	v_cvt_pk_bf16_f32 v26, v26, v27
	v_cvt_pk_bf16_f32 v27, v28, v29
	global_store_dwordx2 v[34:35], v[26:27], off
	s_nop 0
	v_lshl_add_u64 v[34:35], v[2:3], 0, v[10:11]
	v_add_u32_e32 v2, s58, v2
	v_lshlrev_b64 v[34:35], 6, v[34:35]
	v_cmp_lt_i32_e32 vcc, s10, v2
	v_lshl_add_u64 v[34:35], v[14:15], 0, v[34:35]
	s_or_b64 s[40:41], vcc, s[40:41]
	s_waitcnt vmcnt(5)
	v_pk_mul_f32 v[26:27], v[46:47], v[224:225]
	s_waitcnt vmcnt(4)
	v_pk_add_f32 v[30:31], v[228:229], 1.0 op_sel_hi:[1, 0]
	v_pk_mul_f32 v[28:29], v[48:49], v[226:227]
	v_pk_add_f32 v[32:33], v[230:231], 1.0 op_sel_hi:[1, 0]
	s_waitcnt vmcnt(3)
	v_pk_fma_f32 v[26:27], v[26:27], v[30:31], v[232:233]
	v_pk_fma_f32 v[28:29], v[28:29], v[32:33], v[234:235]
	v_cvt_pk_bf16_f32 v26, v26, v27
	v_cvt_pk_bf16_f32 v27, v28, v29
	global_store_dwordx2 v[34:35], v[26:27], off
	s_andn2_b64 exec, exec, s[40:41]
	s_cbranch_execz .LBB0_123

; __device__ void ph_prenorm(const Params& p, int l, int g) {
;     ...
;   for (int row = gw; row < TG; row += nw) {
;     int bl = row / TPB, pp = row % TPB, b = g * GB + bl;
;     const float* src; int mrow;
;     if (pp < CTX) { src = (l == 0 ? p.ctx : p.ctxs) + ((long)b * CTX + pp) * D; mrow = 16; }
;     else { src = (l == 0 ? p.x : p.out) + ((long)b * SEQ + (pp - CTX)) * D; mrow = b; }
;     const float* md = p.mod + ((long)l * 17 + mrow) * 3072;
;     float4 v[4]; float ss = 0.f;
; #pragma unroll
;     for (int i = 0; i < 4; ++i) {
;       v[i] = ((const float4*)src)[lane + 64 * i];
;       ss += v[i].x * v[i].x + v[i].y * v[i].y + v[i].z * v[i].z + v[i].w * v[i].w;
;     }
;     ss = wave_sum(ss);
;     float rs = rsqrtf(ss * (1.f / D) + 1e-6f);
; #pragma unroll
;     for (int i = 0; i < 4; ++i) {
;       int idx = (lane + 64 * i) * 4;
;       float4 g4 = *(const float4*)(p.norm_g + l * D + idx);
;       float4 sh = *(const float4*)(md + idx);
;       float4 sc = *(const float4*)(md + D + idx);
;       float h0 = v[i].x * rs * g4.x * (1.f + sc.x) + sh.x;
;       float h1 = v[i].y * rs * g4.y * (1.f + sc.y) + sh.y;
;       float h2 = v[i].z * rs * g4.z * (1.f + sc.z) + sh.z;
;       float h3 = v[i].w * rs * g4.w * (1.f + sc.w) + sh.w;
;       uint2 o; o.x = pack2(h0, h1); o.y = pack2(h2, h3);
;       *(uint2*)(p.hbuf + ((long)(idx >> 5) * TG + row) * 32 + (idx & 31)) = o;
;     }
;   }
.LBB0_924:
	s_or_b64 exec, exec, s[44:45]
	s_nop 1
	v_readfirstlane_b32 s100, v38
	v_readfirstlane_b32 s101, v39
	s_nop 3
	s_load_dwordx2 s[100:101], s[100:101], 0x0
	v_lshlrev_b64 v[32:33], v36, v[32:33]
	v_lshlrev_b64 v[34:35], 12, v[34:35]
	v_lshl_add_u64 v[30:31], s[90:91], 0, v[30:31]
	s_mov_b64 s[12:13], 0x1000
	v_mov_b32_e32 v23, v1
	v_lshl_add_u64 v[66:67], v[30:31], 0, s[12:13]
	v_lshl_add_u64 v[54:55], v[66:67], 0, v[22:23]
	v_lshl_add_u64 v[68:69], v[30:31], 0, v[22:23]
	v_mov_b32_e32 v29, v1
	s_movk_i32 s10, 0x23ff
	s_waitcnt lgkmcnt(0)
	v_mov_b64_e32 v[38:39], s[100:101]
	v_lshl_add_u64 v[32:33], v[38:39], 0, v[32:33]
	v_lshl_add_u64 v[32:33], v[32:33], 0, v[34:35]
	v_lshl_add_u64 v[50:51], v[32:33], 0, v[0:1]
	global_load_dwordx4 v[32:35], v[50:51], off
	global_load_dwordx4 v[36:39], v[50:51], off offset:1024
	global_load_dwordx4 v[46:49], v[50:51], off offset:2048
	s_nop 0
	global_load_dwordx4 v[50:53], v[50:51], off offset:3072
	s_nop 0
	global_load_dwordx4 v[54:57], v[54:55], off
	s_nop 0
	global_load_dwordx4 v[58:61], v[12:13], off
	global_load_dwordx4 v[62:65], v[68:69], off
	global_load_dwordx4 v[200:203], v[16:17], off
	v_mov_b32_e32 v236, v24
	v_mov_b32_e32 v237, 0
	v_lshl_add_u64 v[236:237], v[66:67], 0, v[236:237]
	global_load_dwordx4 v[204:207], v[236:237], off
	global_load_dwordx4 v[208:211], v[68:69], off offset:1024
	global_load_dwordx4 v[212:215], v[18:19], off
	v_mov_b32_e32 v238, v26
	v_mov_b32_e32 v239, 0
	v_lshl_add_u64 v[238:239], v[66:67], 0, v[238:239]
	global_load_dwordx4 v[216:219], v[238:239], off
	global_load_dwordx4 v[220:223], v[68:69], off offset:2048
	global_load_dwordx4 v[224:227], v[20:21], off
	v_mov_b32_e32 v244, v28
	v_mov_b32_e32 v245, 0
	v_lshl_add_u64 v[244:245], v[66:67], 0, v[244:245]
	global_load_dwordx4 v[228:231], v[244:245], off
	global_load_dwordx4 v[232:235], v[68:69], off offset:3072
	s_waitcnt vmcnt(15)
	v_mov_b32_e32 v74, v33
	s_waitcnt vmcnt(14)
	v_mov_b32_e32 v75, v37
	v_mov_b32_e32 v72, v32
	v_mov_b32_e32 v73, v36
	s_waitcnt vmcnt(13)
	v_mov_b32_e32 v82, v47
	s_waitcnt vmcnt(12)
	v_mov_b32_e32 v83, v51
	v_pk_mul_f32 v[74:75], v[74:75], v[74:75]
	v_mov_b32_e32 v30, v34
	v_mov_b32_e32 v31, v38
	v_mov_b32_e32 v80, v46
	v_mov_b32_e32 v81, v50
	v_pk_mul_f32 v[82:83], v[82:83], v[82:83]
	v_pk_fma_f32 v[72:73], v[72:73], v[72:73], v[74:75]
	v_mov_b32_e32 v70, v35
	v_mov_b32_e32 v71, v39
	v_mov_b32_e32 v76, v48
	v_mov_b32_e32 v77, v52
	v_pk_fma_f32 v[74:75], v[80:81], v[80:81], v[82:83]
	v_pk_fma_f32 v[30:31], v[30:31], v[30:31], v[72:73]
	v_mov_b32_e32 v78, v49
	v_mov_b32_e32 v79, v53
	v_pk_fma_f32 v[72:73], v[76:77], v[76:77], v[74:75]
	v_pk_fma_f32 v[30:31], v[70:71], v[70:71], v[30:31]
	v_pk_fma_f32 v[70:71], v[78:79], v[78:79], v[72:73]
	v_add_f32_e32 v3, v30, v31
	v_add_f32_e32 v3, v3, v70
	v_add_f32_e32 v3, v3, v71
	ds_bpermute_b32 v23, v40, v3
	s_waitcnt vmcnt(11)
	v_pk_add_f32 v[54:55], v[54:55], 1.0 op_sel_hi:[1,0]
	v_pk_add_f32 v[56:57], v[56:57], 1.0 op_sel_hi:[1,0]
	s_waitcnt lgkmcnt(0)
	v_add_f32_e32 v3, v3, v23
	ds_bpermute_b32 v23, v41, v3
	s_waitcnt lgkmcnt(0)
	v_add_f32_e32 v3, v3, v23
	ds_bpermute_b32 v23, v42, v3
	s_waitcnt lgkmcnt(0)
	v_add_f32_e32 v3, v3, v23
	ds_bpermute_b32 v23, v43, v3
	s_waitcnt lgkmcnt(0)
	v_add_f32_e32 v23, v3, v23
	ds_bpermute_b32 v25, v44, v23
	v_ashrrev_i32_e32 v3, 31, v2
	v_lshl_add_u64 v[30:31], v[2:3], 0, v[4:5]
	v_lshlrev_b64 v[30:31], 6, v[30:31]
	v_lshl_add_u64 v[30:31], v[14:15], 0, v[30:31]
	s_waitcnt lgkmcnt(0)
	v_add_f32_e32 v23, v23, v25
	ds_bpermute_b32 v27, v45, v23
	v_mov_b32_e32 v25, v1
	v_lshl_add_u64 v[70:71], v[66:67], 0, v[24:25]
	s_waitcnt lgkmcnt(0)
	v_add_f32_e32 v23, v23, v27
	v_fmamk_f32 v23, v23, 0x3a800000, v168
	v_mul_f32_e32 v25, 0x4b800000, v23
	v_cmp_gt_f32_e32 vcc, s25, v23
	v_mov_b32_e32 v27, v1
	s_nop 0
	v_cndmask_b32_e32 v23, v23, v25, vcc
	v_rsq_f32_e32 v23, v23
	s_nop 0
	v_mul_f32_e32 v25, 0x45800000, v23
	v_cndmask_b32_e32 v72, v23, v25, vcc
	v_pk_mul_f32 v[32:33], v[32:33], v[72:73] op_sel_hi:[1,0]
	v_pk_mul_f32 v[34:35], v[34:35], v[72:73] op_sel_hi:[1,0]
	s_waitcnt vmcnt(10)
	v_pk_mul_f32 v[32:33], v[58:59], v[32:33]
	v_pk_mul_f32 v[34:35], v[60:61], v[34:35]
	s_waitcnt vmcnt(9)
	v_pk_fma_f32 v[32:33], v[54:55], v[32:33], v[62:63]
	v_pk_fma_f32 v[34:35], v[34:35], v[56:57], v[64:65]
	v_cvt_pk_bf16_f32 v32, v32, v33
	v_cvt_pk_bf16_f32 v33, v34, v35
	global_store_dwordx2 v[30:31], v[32:33], off
	s_nop 0
	v_pk_mul_f32 v[36:37], v[36:37], v[72:73] op_sel_hi:[1, 0]
	v_pk_mul_f32 v[38:39], v[38:39], v[72:73] op_sel_hi:[1, 0]
	v_lshl_add_u64 v[34:35], v[2:3], 0, v[6:7]
	v_lshlrev_b64 v[34:35], 6, v[34:35]
	v_lshl_add_u64 v[34:35], v[14:15], 0, v[34:35]
	v_lshl_add_u64 v[62:63], v[66:67], 0, v[26:27]
	v_pk_mul_f32 v[46:47], v[46:47], v[72:73] op_sel_hi:[1, 0]
	v_pk_mul_f32 v[48:49], v[48:49], v[72:73] op_sel_hi:[1, 0]
	v_pk_mul_f32 v[50:51], v[50:51], v[72:73] op_sel_hi:[1, 0]
	v_pk_mul_f32 v[52:53], v[52:53], v[72:73] op_sel_hi:[1, 0]
	s_waitcnt vmcnt(9)
	v_pk_mul_f32 v[30:31], v[36:37], v[200:201]
	s_waitcnt vmcnt(8)
	v_pk_add_f32 v[36:37], v[204:205], 1.0 op_sel_hi:[1, 0]
	v_pk_mul_f32 v[32:33], v[38:39], v[202:203]
	v_pk_add_f32 v[38:39], v[206:207], 1.0 op_sel_hi:[1, 0]
	s_waitcnt vmcnt(7)
	v_pk_fma_f32 v[30:31], v[30:31], v[36:37], v[208:209]
	v_pk_fma_f32 v[32:33], v[32:33], v[38:39], v[210:211]
	v_cvt_pk_bf16_f32 v30, v30, v31
	v_cvt_pk_bf16_f32 v31, v32, v33
	global_store_dwordx2 v[34:35], v[30:31], off
	s_nop 0
	v_lshl_add_u64 v[38:39], v[2:3], 0, v[8:9]
	v_lshlrev_b64 v[38:39], 6, v[38:39]
	v_lshl_add_u64 v[38:39], v[14:15], 0, v[38:39]
	v_lshl_add_u64 v[58:59], v[66:67], 0, v[28:29]
	s_waitcnt vmcnt(7)
	v_pk_mul_f32 v[30:31], v[46:47], v[212:213]
	s_waitcnt vmcnt(6)
	v_pk_add_f32 v[34:35], v[216:217], 1.0 op_sel_hi:[1, 0]
	v_pk_mul_f32 v[32:33], v[48:49], v[214:215]
	v_pk_add_f32 v[36:37], v[218:219], 1.0 op_sel_hi:[1, 0]
	s_waitcnt vmcnt(5)
	v_pk_fma_f32 v[30:31], v[30:31], v[34:35], v[220:221]
	v_pk_fma_f32 v[32:33], v[32:33], v[36:37], v[222:223]
	v_cvt_pk_bf16_f32 v30, v30, v31
	v_cvt_pk_bf16_f32 v31, v32, v33
	global_store_dwordx2 v[38:39], v[30:31], off
	s_nop 0
	v_lshl_add_u64 v[38:39], v[2:3], 0, v[10:11]
	v_add_u32_e32 v2, s58, v2
	v_lshlrev_b64 v[38:39], 6, v[38:39]
	v_cmp_lt_i32_e32 vcc, s10, v2
	v_lshl_add_u64 v[38:39], v[14:15], 0, v[38:39]
	s_or_b64 s[42:43], vcc, s[42:43]
	s_waitcnt vmcnt(5)
	v_pk_mul_f32 v[30:31], v[50:51], v[224:225]
	s_waitcnt vmcnt(4)
	v_pk_add_f32 v[34:35], v[228:229], 1.0 op_sel_hi:[1, 0]
	v_pk_mul_f32 v[32:33], v[52:53], v[226:227]
	v_pk_add_f32 v[36:37], v[230:231], 1.0 op_sel_hi:[1, 0]
	s_waitcnt vmcnt(3)
	v_pk_fma_f32 v[30:31], v[30:31], v[34:35], v[232:233]
	v_pk_fma_f32 v[32:33], v[32:33], v[36:37], v[234:235]
	v_cvt_pk_bf16_f32 v30, v30, v31
	v_cvt_pk_bf16_f32 v31, v32, v33
	global_store_dwordx2 v[38:39], v[30:31], off
	s_andn2_b64 exec, exec, s[42:43]
	s_cbranch_execz .LBB0_929

; __device__ void ph_prenorm(const Params& p, int l, int g) {
;     ...
;   for (int row = gw; row < TG; row += nw) {
;     int bl = row / TPB, pp = row % TPB, b = g * GB + bl;
;     const float* src; int mrow;
;     if (pp < CTX) { src = (l == 0 ? p.ctx : p.ctxs) + ((long)b * CTX + pp) * D; mrow = 16; }
;     else { src = (l == 0 ? p.x : p.out) + ((long)b * SEQ + (pp - CTX)) * D; mrow = b; }
;     const float* md = p.mod + ((long)l * 17 + mrow) * 3072;
;     float4 v[4]; float ss = 0.f;
; #pragma unroll
;     for (int i = 0; i < 4; ++i) {
;       v[i] = ((const float4*)src)[lane + 64 * i];
;       ss += v[i].x * v[i].x + v[i].y * v[i].y + v[i].z * v[i].z + v[i].w * v[i].w;
;     }
;     ss = wave_sum(ss);
;     float rs = rsqrtf(ss * (1.f / D) + 1e-6f);
; #pragma unroll
;     for (int i = 0; i < 4; ++i) {
;       int idx = (lane + 64 * i) * 4;
;       float4 g4 = *(const float4*)(p.norm_g + l * D + idx);
;       float4 sh = *(const float4*)(md + idx);
;       float4 sc = *(const float4*)(md + D + idx);
;       float h0 = v[i].x * rs * g4.x * (1.f + sc.x) + sh.x;
;       float h1 = v[i].y * rs * g4.y * (1.f + sc.y) + sh.y;
;       float h2 = v[i].z * rs * g4.z * (1.f + sc.z) + sh.z;
;       float h3 = v[i].w * rs * g4.w * (1.f + sc.w) + sh.w;
;       uint2 o; o.x = pack2(h0, h1); o.y = pack2(h2, h3);
;       *(uint2*)(p.hbuf + ((long)(idx >> 5) * TG + row) * 32 + (idx & 31)) = o;
;     }
;   }
.LBB0_934:
	s_or_b64 exec, exec, s[44:45]
	v_readlane_b32 s44, v242, 0
	v_readlane_b32 s45, v242, 1
	v_lshlrev_b64 v[28:29], v30, v[28:29]
	v_lshlrev_b64 v[26:27], 12, v[26:27]
	v_lshl_add_u64 v[32:33], s[44:45], 0, v[32:33]
	s_nop 1
	v_readfirstlane_b32 s100, v32
	v_readfirstlane_b32 s101, v33
	s_nop 3
	s_load_dwordx2 s[100:101], s[100:101], 0x0
	v_readlane_b32 s12, v240, 35
	v_readlane_b32 s13, v240, 36
	v_mov_b64_e32 v[48:49], s[90:91]
	v_mov_b32_e32 v17, v1
	v_lshl_add_u64 v[24:25], v[24:25], 0, s[12:13]
	v_mad_u64_u32 v[56:57], s[44:45], v24, s14, v[48:49]
	v_mad_i32_i24 v57, v25, s14, v57
	s_mov_b64 s[12:13], 0x1000
	v_lshl_add_u64 v[60:61], v[56:57], 0, s[12:13]
	v_lshl_add_u64 v[24:25], v[60:61], 0, v[16:17]
	v_lshl_add_u64 v[62:63], v[56:57], 0, v[16:17]
	v_mov_b32_e32 v23, v1
	s_movk_i32 s10, 0x23ff
	s_waitcnt lgkmcnt(0)
	v_mov_b64_e32 v[32:33], s[100:101]
	v_lshl_add_u64 v[28:29], v[32:33], 0, v[28:29]
	v_lshl_add_u64 v[26:27], v[28:29], 0, v[26:27]
	v_lshl_add_u64 v[44:45], v[26:27], 0, v[0:1]
	global_load_dwordx4 v[26:29], v[44:45], off
	global_load_dwordx4 v[30:33], v[44:45], off offset:1024
	global_load_dwordx4 v[40:43], v[44:45], off offset:2048
	s_nop 0
	global_load_dwordx4 v[44:47], v[44:45], off offset:3072
	s_nop 0
	global_load_dwordx4 v[48:51], v[24:25], off
	global_load_dwordx4 v[52:55], v[12:13], off
	global_load_dwordx4 v[56:59], v[62:63], off
	global_load_dwordx4 v[200:203], v[12:13], off offset:1024
	v_mov_b32_e32 v236, v18
	v_mov_b32_e32 v237, 0
	v_lshl_add_u64 v[236:237], v[60:61], 0, v[236:237]
	global_load_dwordx4 v[204:207], v[236:237], off
	global_load_dwordx4 v[208:211], v[62:63], off offset:1024
	global_load_dwordx4 v[212:215], v[12:13], off offset:2048
	v_mov_b32_e32 v238, v20
	v_mov_b32_e32 v239, 0
	v_lshl_add_u64 v[238:239], v[60:61], 0, v[238:239]
	global_load_dwordx4 v[216:219], v[238:239], off
	global_load_dwordx4 v[220:223], v[62:63], off offset:2048
	global_load_dwordx4 v[224:227], v[12:13], off offset:3072
	v_mov_b32_e32 v244, v22
	v_mov_b32_e32 v245, 0
	v_lshl_add_u64 v[244:245], v[60:61], 0, v[244:245]
	global_load_dwordx4 v[228:231], v[244:245], off
	global_load_dwordx4 v[232:235], v[62:63], off offset:3072
	s_waitcnt vmcnt(15)
	v_mov_b32_e32 v68, v27
	s_waitcnt vmcnt(14)
	v_mov_b32_e32 v69, v31
	v_mov_b32_e32 v66, v26
	v_mov_b32_e32 v67, v30
	s_waitcnt vmcnt(13)
	v_mov_b32_e32 v76, v41
	s_waitcnt vmcnt(12)
	v_mov_b32_e32 v77, v45
	v_pk_mul_f32 v[68:69], v[68:69], v[68:69]
	v_mov_b32_e32 v24, v28
	v_mov_b32_e32 v25, v32
	v_mov_b32_e32 v74, v40
	v_mov_b32_e32 v75, v44
	v_pk_mul_f32 v[76:77], v[76:77], v[76:77]
	v_pk_fma_f32 v[66:67], v[66:67], v[66:67], v[68:69]
	v_mov_b32_e32 v64, v29
	v_mov_b32_e32 v65, v33
	v_mov_b32_e32 v70, v42
	v_mov_b32_e32 v71, v46
	v_pk_fma_f32 v[68:69], v[74:75], v[74:75], v[76:77]
	v_pk_fma_f32 v[24:25], v[24:25], v[24:25], v[66:67]
	v_mov_b32_e32 v72, v43
	v_mov_b32_e32 v73, v47
	v_pk_fma_f32 v[66:67], v[70:71], v[70:71], v[68:69]
	v_pk_fma_f32 v[24:25], v[64:65], v[64:65], v[24:25]
	v_pk_fma_f32 v[64:65], v[72:73], v[72:73], v[66:67]
	v_add_f32_e32 v3, v24, v25
	v_add_f32_e32 v3, v3, v64
	v_add_f32_e32 v3, v3, v65
	ds_bpermute_b32 v17, v34, v3
	s_waitcnt vmcnt(11)
	v_pk_add_f32 v[48:49], v[48:49], 1.0 op_sel_hi:[1,0]
	v_pk_add_f32 v[50:51], v[50:51], 1.0 op_sel_hi:[1,0]
	s_waitcnt lgkmcnt(0)
	v_add_f32_e32 v3, v3, v17
	ds_bpermute_b32 v17, v35, v3
	s_waitcnt lgkmcnt(0)
	v_add_f32_e32 v3, v3, v17
	ds_bpermute_b32 v17, v36, v3
	s_waitcnt lgkmcnt(0)
	v_add_f32_e32 v3, v3, v17
	ds_bpermute_b32 v17, v37, v3
	s_waitcnt lgkmcnt(0)
; __device__ void ph_prenorm(const Params& p, int l, int g) {
;     ...
;   for (int row = gw; row < TG; row += nw) {
;     int bl = row / TPB, pp = row % TPB, b = g * GB + bl;
;     const float* src; int mrow;
;     if (pp < CTX) { src = (l == 0 ? p.ctx : p.ctxs) + ((long)b * CTX + pp) * D; mrow = 16; }
;     else { src = (l == 0 ? p.x : p.out) + ((long)b * SEQ + (pp - CTX)) * D; mrow = b; }
;     const float* md = p.mod + ((long)l * 17 + mrow) * 3072;
;     float4 v[4]; float ss = 0.f;
; #pragma unroll
;     for (int i = 0; i < 4; ++i) {
;       v[i] = ((const float4*)src)[lane + 64 * i];
;       ss += v[i].x * v[i].x + v[i].y * v[i].y + v[i].z * v[i].z + v[i].w * v[i].w;
;     }
;     ss = wave_sum(ss);
;     float rs = rsqrtf(ss * (1.f / D) + 1e-6f);
; #pragma unroll
;     for (int i = 0; i < 4; ++i) {
;       int idx = (lane + 64 * i) * 4;
;       float4 g4 = *(const float4*)(p.norm_g + l * D + idx);
;       float4 sh = *(const float4*)(md + idx);
;       float4 sc = *(const float4*)(md + D + idx);
;       float h0 = v[i].x * rs * g4.x * (1.f + sc.x) + sh.x;
;       float h1 = v[i].y * rs * g4.y * (1.f + sc.y) + sh.y;
;       float h2 = v[i].z * rs * g4.z * (1.f + sc.z) + sh.z;
;       float h3 = v[i].w * rs * g4.w * (1.f + sc.w) + sh.w;
;       uint2 o; o.x = pack2(h0, h1); o.y = pack2(h2, h3);
;       *(uint2*)(p.hbuf + ((long)(idx >> 5) * TG + row) * 32 + (idx & 31)) = o;
;     }
;   }
	v_add_f32_e32 v17, v3, v17
	ds_bpermute_b32 v19, v38, v17
	v_ashrrev_i32_e32 v3, 31, v2
	v_lshl_add_u64 v[24:25], v[2:3], 0, v[4:5]
	v_lshlrev_b64 v[24:25], 6, v[24:25]
	v_lshl_add_u64 v[24:25], v[14:15], 0, v[24:25]
	s_waitcnt lgkmcnt(0)
	v_add_f32_e32 v17, v17, v19
	ds_bpermute_b32 v21, v39, v17
	v_mov_b32_e32 v19, v1
	v_lshl_add_u64 v[64:65], v[60:61], 0, v[18:19]
	s_waitcnt lgkmcnt(0)
	v_add_f32_e32 v17, v17, v21
	v_fmamk_f32 v17, v17, 0x3a800000, v168
	v_mul_f32_e32 v21, 0x4b800000, v17
	v_cmp_gt_f32_e32 vcc, s25, v17
	s_nop 1
	v_cndmask_b32_e32 v17, v17, v21, vcc
	v_rsq_f32_e32 v17, v17
	v_mov_b32_e32 v21, v1
	v_mul_f32_e32 v19, 0x45800000, v17
	v_cndmask_b32_e32 v66, v17, v19, vcc
	v_pk_mul_f32 v[26:27], v[26:27], v[66:67] op_sel_hi:[1,0]
	v_pk_mul_f32 v[28:29], v[28:29], v[66:67] op_sel_hi:[1,0]
	s_waitcnt vmcnt(10)
	v_pk_mul_f32 v[26:27], v[52:53], v[26:27]
	v_pk_mul_f32 v[28:29], v[54:55], v[28:29]
	s_waitcnt vmcnt(9)
	v_pk_fma_f32 v[26:27], v[48:49], v[26:27], v[56:57]
	v_pk_fma_f32 v[28:29], v[28:29], v[50:51], v[58:59]
	v_cvt_pk_bf16_f32 v26, v26, v27
	v_cvt_pk_bf16_f32 v27, v28, v29
	global_store_dwordx2 v[24:25], v[26:27], off
	s_nop 0
	v_pk_mul_f32 v[30:31], v[30:31], v[66:67] op_sel_hi:[1, 0]
	v_pk_mul_f32 v[32:33], v[32:33], v[66:67] op_sel_hi:[1, 0]
	v_lshl_add_u64 v[28:29], v[2:3], 0, v[6:7]
	v_lshlrev_b64 v[28:29], 6, v[28:29]
	v_lshl_add_u64 v[28:29], v[14:15], 0, v[28:29]
	v_lshl_add_u64 v[56:57], v[60:61], 0, v[20:21]
	v_pk_mul_f32 v[40:41], v[40:41], v[66:67] op_sel_hi:[1, 0]
	v_pk_mul_f32 v[42:43], v[42:43], v[66:67] op_sel_hi:[1, 0]
	v_pk_mul_f32 v[44:45], v[44:45], v[66:67] op_sel_hi:[1, 0]
	v_pk_mul_f32 v[46:47], v[46:47], v[66:67] op_sel_hi:[1, 0]
	s_waitcnt vmcnt(9)
	v_pk_mul_f32 v[24:25], v[30:31], v[200:201]
	s_waitcnt vmcnt(8)
	v_pk_add_f32 v[30:31], v[204:205], 1.0 op_sel_hi:[1, 0]
	v_pk_mul_f32 v[26:27], v[32:33], v[202:203]
	v_pk_add_f32 v[32:33], v[206:207], 1.0 op_sel_hi:[1, 0]
	s_waitcnt vmcnt(7)
	v_pk_fma_f32 v[24:25], v[24:25], v[30:31], v[208:209]
	v_pk_fma_f32 v[26:27], v[26:27], v[32:33], v[210:211]
	v_cvt_pk_bf16_f32 v24, v24, v25
	v_cvt_pk_bf16_f32 v25, v26, v27
	global_store_dwordx2 v[28:29], v[24:25], off
	s_nop 0
	v_lshl_add_u64 v[32:33], v[2:3], 0, v[8:9]
	v_lshlrev_b64 v[32:33], 6, v[32:33]
	v_lshl_add_u64 v[32:33], v[14:15], 0, v[32:33]
	v_lshl_add_u64 v[52:53], v[60:61], 0, v[22:23]
	s_waitcnt vmcnt(7)
	v_pk_mul_f32 v[24:25], v[40:41], v[212:213]
	s_waitcnt vmcnt(6)
	v_pk_add_f32 v[28:29], v[216:217], 1.0 op_sel_hi:[1, 0]
	v_pk_mul_f32 v[26:27], v[42:43], v[214:215]
	v_pk_add_f32 v[30:31], v[218:219], 1.0 op_sel_hi:[1, 0]
	s_waitcnt vmcnt(5)
	v_pk_fma_f32 v[24:25], v[24:25], v[28:29], v[220:221]
	v_pk_fma_f32 v[26:27], v[26:27], v[30:31], v[222:223]
	v_cvt_pk_bf16_f32 v24, v24, v25
	v_cvt_pk_bf16_f32 v25, v26, v27
	global_store_dwordx2 v[32:33], v[24:25], off
	s_nop 0
	v_lshl_add_u64 v[32:33], v[2:3], 0, v[10:11]
	v_add_u32_e32 v2, s58, v2
	v_lshlrev_b64 v[32:33], 6, v[32:33]
	v_cmp_lt_i32_e32 vcc, s10, v2
	v_lshl_add_u64 v[32:33], v[14:15], 0, v[32:33]
	s_or_b64 s[42:43], vcc, s[42:43]
	s_waitcnt vmcnt(5)
	v_pk_mul_f32 v[24:25], v[44:45], v[224:225]
	s_waitcnt vmcnt(4)
	v_pk_add_f32 v[28:29], v[228:229], 1.0 op_sel_hi:[1, 0]
	v_pk_mul_f32 v[26:27], v[46:47], v[226:227]
	v_pk_add_f32 v[30:31], v[230:231], 1.0 op_sel_hi:[1, 0]
	s_waitcnt vmcnt(3)
	v_pk_fma_f32 v[24:25], v[24:25], v[28:29], v[232:233]
	v_pk_fma_f32 v[26:27], v[26:27], v[30:31], v[234:235]
	v_cvt_pk_bf16_f32 v24, v24, v25
	v_cvt_pk_bf16_f32 v25, v26, v27
	global_store_dwordx2 v[32:33], v[24:25], off
	s_andn2_b64 exec, exec, s[42:43]
	s_cbranch_execz .LBB0_939

; __device__ __forceinline__ int otid() { int t = threadIdx.x; asm volatile("" : "+v"(t)); return t; }
; __device__ void ph_final(const Params& p) {
;   const int tid = otid();
;   const int lane = tid & 63;
;   const int gw = blockIdx.x * 4 + (tid >> 6), nw = gridDim.x * 4;
;   for (int row = gw; row < NB * SEQ; row += nw) {
;     float4* src = (float4*)(p.out + (long)row * D);
;     float4 v[4]; float ss = 0.f;
; #pragma unroll
;     for (int i = 0; i < 4; ++i) {
;       v[i] = src[lane + 64 * i];
;       ss += v[i].x * v[i].x + v[i].y * v[i].y + v[i].z * v[i].z + v[i].w * v[i].w;
;     }
;     ss = wave_sum(ss);
;     float rs = rsqrtf(ss * (1.f / D) + 1e-6f);
; #pragma unroll
;     for (int i = 0; i < 4; ++i) {
;       float4 g4 = ((const float4*)p.final_g)[lane + 64 * i];
;       float4 o; o.x = v[i].x * rs * g4.x; o.y = v[i].y * rs * g4.y; o.z = v[i].z * rs * g4.z; o.w = v[i].w * rs * g4.w;
;       src[lane + 64 * i] = o;
;     }
;   }
; }
.LBB0_1215:
	v_readlane_b32 s0, v241, 2
	v_ashrrev_i32_e32 v0, 6, v156
	s_nop 0
	v_add_u32_e32 v0, s0, v0
	s_mov_b32 s0, 0x8000
	v_cmp_gt_i32_e32 vcc, s0, v0
	s_and_saveexec_b64 s[0:1], vcc
	s_cbranch_execz .LBB0_1218
	v_cmp_lt_i32_e32 vcc, v164, v158
	v_readlane_b32 s4, v242, 0
	v_readlane_b32 s5, v242, 1
	v_cndmask_b32_e32 v1, v157, v164, vcc
	v_cmp_lt_i32_e32 vcc, v163, v158
	v_lshlrev_b32_e32 v6, 2, v1
	s_load_dwordx4 s[0:3], s[4:5], 0x98
	v_cndmask_b32_e32 v1, v157, v163, vcc
	v_cmp_lt_i32_e32 vcc, v162, v158
	v_lshlrev_b32_e32 v7, 2, v1
	v_mov_b32_e32 v5, 0
	v_cndmask_b32_e32 v1, v157, v162, vcc
	v_cmp_lt_i32_e32 vcc, v161, v158
	v_lshlrev_b32_e32 v8, 2, v1
	s_ashr_i32 s59, s58, 31
	v_cndmask_b32_e32 v1, v157, v161, vcc
	v_cmp_lt_i32_e32 vcc, v160, v158
	v_lshlrev_b32_e32 v9, 2, v1
	s_mov_b32 s4, 0x800000
	v_cndmask_b32_e32 v1, v157, v160, vcc
	v_cmp_lt_i32_e32 vcc, v159, v158
	v_lshlrev_b32_e32 v10, 2, v1
	s_movk_i32 s5, 0x7fff
	v_cndmask_b32_e32 v1, v157, v159, vcc
	v_lshlrev_b32_e32 v11, 2, v1
	v_lshlrev_b32_e32 v1, 4, v156
	v_and_b32_e32 v4, 0x3f0, v1
	v_ashrrev_i32_e32 v1, 31, v0
	v_lshlrev_b64 v[12:13], 12, v[0:1]
	v_or_b32_e32 v12, v12, v4
	s_waitcnt lgkmcnt(0)
	v_lshl_add_u64 v[2:3], s[0:1], 0, v[4:5]
	v_lshl_add_u64 v[4:5], s[2:3], 0, v[12:13]
	s_mov_b64 s[0:1], 0x800
	v_lshl_add_u64 v[4:5], v[4:5], 0, s[0:1]
	s_lshl_b64 s[0:1], s[58:59], 12
	s_mov_b64 s[2:3], 0
	v_mov_b32_e32 v1, 0x358637bd
	global_load_dwordx4 v[48:51], v[2:3], off
	global_load_dwordx4 v[52:55], v[2:3], off offset:1024
	global_load_dwordx4 v[56:59], v[2:3], off offset:2048
	global_load_dwordx4 v[60:63], v[2:3], off offset:3072
.LBB0_1217:
	global_load_dwordx4 v[12:15], v[4:5], off offset:-2048
	global_load_dwordx4 v[16:19], v[4:5], off offset:-1024
	global_load_dwordx4 v[20:23], v[4:5], off
	global_load_dwordx4 v[24:27], v[4:5], off offset:1024
	v_add_u32_e32 v0, s58, v0
	s_waitcnt vmcnt(3)
	v_mov_b32_e32 v34, v13
	s_waitcnt vmcnt(2)
	v_mov_b32_e32 v35, v17
	v_mov_b32_e32 v32, v12
	v_mov_b32_e32 v33, v16
	s_waitcnt vmcnt(1)
	v_mov_b32_e32 v42, v21
	s_waitcnt vmcnt(0)
	v_mov_b32_e32 v43, v25
	v_pk_mul_f32 v[34:35], v[34:35], v[34:35]
	v_mov_b32_e32 v36, v14
	v_mov_b32_e32 v37, v18
	v_mov_b32_e32 v40, v20
	v_mov_b32_e32 v41, v24
	v_pk_mul_f32 v[42:43], v[42:43], v[42:43]
	v_pk_fma_f32 v[32:33], v[32:33], v[32:33], v[34:35]
	v_mov_b32_e32 v38, v15
	v_mov_b32_e32 v39, v19
	v_mov_b32_e32 v44, v22
	v_mov_b32_e32 v45, v26
	v_pk_fma_f32 v[34:35], v[40:41], v[40:41], v[42:43]
	v_pk_fma_f32 v[32:33], v[36:37], v[36:37], v[32:33]
	v_mov_b32_e32 v46, v23
	v_mov_b32_e32 v47, v27
	v_pk_fma_f32 v[34:35], v[44:45], v[44:45], v[34:35]
	v_pk_fma_f32 v[32:33], v[38:39], v[38:39], v[32:33]
	v_pk_fma_f32 v[34:35], v[46:47], v[46:47], v[34:35]
	v_add_f32_e32 v32, v32, v33
	v_add_f32_e32 v32, v32, v34
	v_add_f32_e32 v32, v32, v35
	ds_bpermute_b32 v33, v6, v32
	s_waitcnt lgkmcnt(0)
	v_add_f32_e32 v32, v32, v33
	ds_bpermute_b32 v33, v7, v32
	s_waitcnt lgkmcnt(0)
	v_add_f32_e32 v32, v32, v33
	ds_bpermute_b32 v33, v8, v32
	s_waitcnt lgkmcnt(0)
	v_add_f32_e32 v32, v32, v33
	ds_bpermute_b32 v33, v9, v32
	s_waitcnt lgkmcnt(0)
	v_add_f32_e32 v32, v32, v33
	ds_bpermute_b32 v33, v10, v32
	s_waitcnt lgkmcnt(0)
	v_add_f32_e32 v32, v32, v33
	ds_bpermute_b32 v33, v11, v32
	s_waitcnt lgkmcnt(0)
	v_add_f32_e32 v32, v32, v33
	v_fmamk_f32 v32, v32, 0x3a800000, v1
	v_mul_f32_e32 v33, 0x4b800000, v32
	v_cmp_gt_f32_e32 vcc, s4, v32
	s_nop 1
	v_cndmask_b32_e32 v32, v32, v33, vcc
	v_rsq_f32_e32 v32, v32
	s_nop 0
	v_mul_f32_e32 v33, 0x45800000, v32
	v_cndmask_b32_e32 v32, v32, v33, vcc
	v_pk_mul_f32 v[12:13], v[12:13], v[32:33] op_sel_hi:[1,0]
	v_pk_mul_f32 v[14:15], v[14:15], v[32:33] op_sel_hi:[1,0]
	v_pk_mul_f32 v[12:13], v[48:49], v[12:13]
	v_pk_mul_f32 v[14:15], v[50:51], v[14:15]
	global_store_dwordx4 v[4:5], v[12:15], off offset:-2048
	v_pk_mul_f32 v[16:17], v[16:17], v[32:33] op_sel_hi:[1,0]
	v_pk_mul_f32 v[18:19], v[18:19], v[32:33] op_sel_hi:[1,0]
	v_cmp_lt_i32_e32 vcc, s5, v0
	s_or_b64 s[2:3], vcc, s[2:3]
	v_pk_mul_f32 v[12:13], v[52:53], v[16:17]
	v_pk_mul_f32 v[14:15], v[18:19], v[54:55]
	global_store_dwordx4 v[4:5], v[12:15], off offset:-1024
	v_pk_mul_f32 v[16:17], v[20:21], v[32:33] op_sel_hi:[1,0]
	v_pk_mul_f32 v[18:19], v[22:23], v[32:33] op_sel_hi:[1,0]
	v_pk_mul_f32 v[12:13], v[16:17], v[56:57]
	v_pk_mul_f32 v[14:15], v[18:19], v[58:59]
	global_store_dwordx4 v[4:5], v[12:15], off
	v_pk_mul_f32 v[16:17], v[24:25], v[32:33] op_sel_hi:[1,0]
	v_pk_mul_f32 v[18:19], v[26:27], v[32:33] op_sel_hi:[1,0]
	v_pk_mul_f32 v[12:13], v[16:17], v[60:61]
	v_pk_mul_f32 v[14:15], v[18:19], v[62:63]
	global_store_dwordx4 v[4:5], v[12:15], off offset:1024
	v_lshl_add_u64 v[4:5], v[4:5], 0, s[0:1]
	s_andn2_b64 exec, exec, s[2:3]
	s_cbranch_execnz .LBB0_1217
